# v044 + EpiRes: the eight 16-lane ss float atomics per wave-tile merged into two 64-lane atomics (lane fq keeps row group fq)
# speedup vs baseline: 1.0158x; 1.0158x over previous
; __device__ __forceinline__ unsigned cvt_pk_bf16(float lo, float hi) { unsigned r; asm volatile("v_cvt_pk_bf16_f32 %0, %1, %2" : "=v"(r) : "v"(lo), "v"(hi)); return r; }
; __device__ __forceinline__ void st16f_wt(void* p, f32x4 v) { asm volatile("global_store_dwordx4 %0, %1, off sc1\n\ts_nop 1" :: "v"(p), "v"(v) : "memory"); }
; __device__ __forceinline__ void st8_wt(void* p, u32x2w v) { asm volatile("global_store_dwordx2 %0, %1, off sc1\n\ts_nop 1" :: "v"(p), "v"(v) : "memory"); }
;     __device__ __forceinline__ void operator()(const f32x4 (&acc)[2][2][4][2], const Unit& u, int wr, int wc, int fr, int fq) const {
;     ...
;                 for (int n = 0; n < 2; ++n) { f32x4 x = xc[bj][n] + (acc[ai][bj][m][n] + bv[bj][n]) * alpha; st16f_wt(X + off + bj * HALF + n * 16, x);
;                     if (XB) { u32x2w w; w.x = cvt_pk_bf16(x[0], x[1]); w.y = cvt_pk_bf16(x[2], x[3]); st8_wt(XB + off + bj * HALF + n * 16, w); }
;                     s += (x[0] * x[0] + x[1] * x[1]) + (x[2] * x[2] + x[3] * x[3]); }
;             if (ssout) { s += __shfl_xor(s, 16); s += __shfl_xor(s, 32); if (fq == 0) unsafeAtomicAdd(ssout + row, s); } }
.LBB0_540:
	v_cndmask_b32_e64 v196, 0, 1, s[90:91]
	v_cmp_ne_u32_e64 s[58:59], 1, v196
	s_andn2_b64 vcc, exec, s[90:91]
	s_cbranch_vccnz .LBB0_544
	v_mul_f32_e32 v175, v175, v175
	v_fmac_f32_e32 v175, v174, v174
	v_mul_f32_e32 v174, v176, v176
	v_fmac_f32_e32 v174, v177, v177
	v_mul_f32_e32 v151, v151, v151
	v_add_f32_e32 v174, v175, v174
	v_mul_f32_e32 v175, v187, v187
	v_mul_f32_e32 v176, v188, v188
	v_mul_f32_e32 v163, v163, v163
	v_fmac_f32_e32 v151, v150, v150
	v_mul_f32_e32 v150, v152, v152
	v_fmac_f32_e32 v175, v186, v186
	v_fmac_f32_e32 v176, v189, v189
	v_fmac_f32_e32 v163, v162, v162
	v_mul_f32_e32 v162, v164, v164
	v_fmac_f32_e32 v150, v153, v153
	v_and_b32_e32 v152, 64, v233
	v_add_f32_e32 v175, v175, v176
	v_fmac_f32_e32 v162, v165, v165
	v_add_f32_e32 v150, v151, v150
	v_xor_b32_e32 v151, 16, v233
	v_add_u32_e32 v152, 64, v152
	v_add_f32_e32 v174, v174, v175
	v_add_f32_e32 v162, v163, v162
	v_cmp_lt_i32_e32 vcc, v151, v152
	v_add_f32_e32 v162, v174, v162
	v_add_f32_e32 v150, v162, v150
	v_cndmask_b32_e32 v151, v233, v151, vcc
	v_lshlrev_b32_e32 v151, 2, v151
	ds_bpermute_b32 v151, v151, v150
	s_waitcnt lgkmcnt(0)
	v_add_f32_e32 v150, v150, v151
	v_xor_b32_e32 v151, 32, v233
	v_cmp_lt_i32_e32 vcc, v151, v152
	s_nop 1
	v_cndmask_b32_e32 v151, v233, v151, vcc
	v_lshlrev_b32_e32 v151, 2, v151
	ds_bpermute_b32 v151, v151, v150
	s_waitcnt lgkmcnt(0)
	v_add_f32_e32 v150, v150, v151
	s_mov_b32 s2, 0xffff
	s_mov_b32 s3, 0
	v_cndmask_b32_e64 v243, v243, v150, s[2:3]
.LBB0_543:
.LBB0_544:
	v_or_b32_e32 v222, 48, v214
	s_mov_b64 s[2:3], -1
	s_and_b64 vcc, exec, s[60:61]
	v_mov_b64_e32 v[152:153], s[68:69]
	s_cbranch_vccnz .LBB0_550
	s_movk_i32 s2, 0x7fff
	v_cmp_lt_i32_e32 vcc, s2, v222
	s_and_saveexec_b64 s[2:3], vcc
	s_xor_b64 s[2:3], exec, s[2:3]
	s_cbranch_execz .LBB0_547
	v_add_u32_e32 v150, 0xffff8030, v214
	s_waitcnt lgkmcnt(0)
	v_mov_b32_e32 v151, v0

; __device__ __forceinline__ unsigned cvt_pk_bf16(float lo, float hi) { unsigned r; asm volatile("v_cvt_pk_bf16_f32 %0, %1, %2" : "=v"(r) : "v"(lo), "v"(hi)); return r; }
; __device__ __forceinline__ void st16f_wt(void* p, f32x4 v) { asm volatile("global_store_dwordx4 %0, %1, off sc1\n\ts_nop 1" :: "v"(p), "v"(v) : "memory"); }
; __device__ __forceinline__ void st8_wt(void* p, u32x2w v) { asm volatile("global_store_dwordx2 %0, %1, off sc1\n\ts_nop 1" :: "v"(p), "v"(v) : "memory"); }
;     __device__ __forceinline__ void operator()(const f32x4 (&acc)[2][2][4][2], const Unit& u, int wr, int wc, int fr, int fq) const {
;     ...
;                 for (int n = 0; n < 2; ++n) { f32x4 x = xc[bj][n] + (acc[ai][bj][m][n] + bv[bj][n]) * alpha; st16f_wt(X + off + bj * HALF + n * 16, x);
;                     if (XB) { u32x2w w; w.x = cvt_pk_bf16(x[0], x[1]); w.y = cvt_pk_bf16(x[2], x[3]); st8_wt(XB + off + bj * HALF + n * 16, w); }
;                     s += (x[0] * x[0] + x[1] * x[1]) + (x[2] * x[2] + x[3] * x[3]); }
;             if (ssout) { s += __shfl_xor(s, 16); s += __shfl_xor(s, 32); if (fq == 0) unsafeAtomicAdd(ssout + row, s); } }
.LBB0_560:
	s_and_b64 vcc, exec, s[58:59]
	s_cbranch_vccnz .LBB0_564
	v_mul_f32_e32 v191, v191, v191
	v_mul_f32_e32 v179, v179, v179
	v_mul_f32_e32 v155, v155, v155
	v_fmac_f32_e32 v191, v190, v190
	v_mul_f32_e32 v190, v192, v192
	v_fmac_f32_e32 v179, v178, v178
	v_mul_f32_e32 v178, v180, v180
	v_mul_f32_e32 v167, v167, v167
	v_fmac_f32_e32 v155, v154, v154
	v_mul_f32_e32 v154, v156, v156
	v_fmac_f32_e32 v190, v193, v193
	v_fmac_f32_e32 v178, v181, v181
	v_fmac_f32_e32 v167, v166, v166
	v_mul_f32_e32 v166, v168, v168
	v_fmac_f32_e32 v154, v157, v157
	v_and_b32_e32 v156, 64, v233
	v_add_f32_e32 v190, v191, v190
	v_add_f32_e32 v178, v179, v178
	v_fmac_f32_e32 v166, v169, v169
	v_add_f32_e32 v154, v155, v154
	v_xor_b32_e32 v155, 16, v233
	v_add_u32_e32 v156, 64, v156
	v_add_f32_e32 v178, v190, v178
	v_add_f32_e32 v166, v167, v166
	v_cmp_lt_i32_e32 vcc, v155, v156
	v_add_f32_e32 v166, v178, v166
	v_add_f32_e32 v154, v166, v154
	v_cndmask_b32_e32 v155, v233, v155, vcc
	v_lshlrev_b32_e32 v155, 2, v155
	ds_bpermute_b32 v155, v155, v154
	s_waitcnt lgkmcnt(0)
	v_add_f32_e32 v154, v154, v155
	v_xor_b32_e32 v155, 32, v233
	v_cmp_lt_i32_e32 vcc, v155, v156
	s_nop 1
	v_cndmask_b32_e32 v155, v233, v155, vcc
	v_lshlrev_b32_e32 v155, 2, v155
	ds_bpermute_b32 v155, v155, v154
	s_waitcnt lgkmcnt(0)
	v_add_f32_e32 v154, v154, v155
	s_mov_b32 s2, 0xffff0000
	s_mov_b32 s3, 0
	v_cndmask_b32_e64 v243, v243, v154, s[2:3]
.LBB0_563:
.LBB0_564:
	v_add_u32_e32 v206, 0x80, v214
	s_mov_b64 s[2:3], -1
	s_and_b64 vcc, exec, s[60:61]
	v_mov_b64_e32 v[156:157], s[68:69]
	s_cbranch_vccnz .LBB0_570
	s_movk_i32 s2, 0x7f7f
	v_cmp_lt_i32_e32 vcc, s2, v214
	s_and_saveexec_b64 s[2:3], vcc
	s_xor_b64 s[2:3], exec, s[2:3]
	s_cbranch_execz .LBB0_567
	v_add_u32_e32 v154, 0xffff8080, v214
	s_waitcnt lgkmcnt(0)
	v_mov_b32_e32 v155, v0

; __device__ __forceinline__ unsigned cvt_pk_bf16(float lo, float hi) { unsigned r; asm volatile("v_cvt_pk_bf16_f32 %0, %1, %2" : "=v"(r) : "v"(lo), "v"(hi)); return r; }
; __device__ __forceinline__ void st16f_wt(void* p, f32x4 v) { asm volatile("global_store_dwordx4 %0, %1, off sc1\n\ts_nop 1" :: "v"(p), "v"(v) : "memory"); }
; __device__ __forceinline__ void st8_wt(void* p, u32x2w v) { asm volatile("global_store_dwordx2 %0, %1, off sc1\n\ts_nop 1" :: "v"(p), "v"(v) : "memory"); }
;     __device__ __forceinline__ void operator()(const f32x4 (&acc)[2][2][4][2], const Unit& u, int wr, int wc, int fr, int fq) const {
;     ...
;                 for (int n = 0; n < 2; ++n) { f32x4 x = xc[bj][n] + (acc[ai][bj][m][n] + bv[bj][n]) * alpha; st16f_wt(X + off + bj * HALF + n * 16, x);
;                     if (XB) { u32x2w w; w.x = cvt_pk_bf16(x[0], x[1]); w.y = cvt_pk_bf16(x[2], x[3]); st8_wt(XB + off + bj * HALF + n * 16, w); }
;                     s += (x[0] * x[0] + x[1] * x[1]) + (x[2] * x[2] + x[3] * x[3]); }
;             if (ssout) { s += __shfl_xor(s, 16); s += __shfl_xor(s, 32); if (fq == 0) unsafeAtomicAdd(ssout + row, s); } }
.LBB0_580:
	s_and_b64 vcc, exec, s[58:59]
	s_cbranch_vccnz .LBB0_584
	v_mul_f32_e32 v183, v183, v183
	v_mul_f32_e32 v171, v171, v171
	v_mul_f32_e32 v147, v147, v147
	v_fmac_f32_e32 v183, v182, v182
	v_mul_f32_e32 v182, v184, v184
	v_fmac_f32_e32 v171, v170, v170
	v_mul_f32_e32 v170, v172, v172
	v_mul_f32_e32 v159, v159, v159
	v_fmac_f32_e32 v147, v146, v146
	v_mul_f32_e32 v146, v148, v148
	v_fmac_f32_e32 v182, v185, v185
	v_fmac_f32_e32 v170, v173, v173
	v_fmac_f32_e32 v159, v158, v158
	v_mul_f32_e32 v158, v160, v160
	v_fmac_f32_e32 v146, v149, v149
	v_and_b32_e32 v148, 64, v233
	v_add_f32_e32 v182, v183, v182
	v_add_f32_e32 v170, v171, v170
	v_fmac_f32_e32 v158, v161, v161
	v_add_f32_e32 v146, v147, v146
	v_xor_b32_e32 v147, 16, v233
	v_add_u32_e32 v148, 64, v148
	v_add_f32_e32 v170, v182, v170
	v_add_f32_e32 v158, v159, v158
	v_cmp_lt_i32_e32 vcc, v147, v148
	v_add_f32_e32 v158, v170, v158
	v_add_f32_e32 v146, v158, v146
	v_cndmask_b32_e32 v147, v233, v147, vcc
	v_lshlrev_b32_e32 v147, 2, v147
	ds_bpermute_b32 v147, v147, v146
	s_waitcnt lgkmcnt(0)
	v_add_f32_e32 v146, v146, v147
	v_xor_b32_e32 v147, 32, v233
	v_cmp_lt_i32_e32 vcc, v147, v148
	s_nop 1
	v_cndmask_b32_e32 v147, v233, v147, vcc
	v_lshlrev_b32_e32 v147, 2, v147
	ds_bpermute_b32 v147, v147, v146
	s_waitcnt lgkmcnt(0)
	v_add_f32_e32 v146, v146, v147
	s_mov_b32 s2, 0
	s_mov_b32 s3, 0xffff
	v_cndmask_b32_e64 v243, v243, v146, s[2:3]
.LBB0_583:
.LBB0_584:
	v_add_u32_e32 v146, 0x90, v214
	s_mov_b64 s[2:3], -1
	s_and_b64 vcc, exec, s[60:61]
	v_mov_b64_e32 v[158:159], s[68:69]
	s_cbranch_vccnz .LBB0_590
	s_movk_i32 s2, 0x7f6f
	v_cmp_lt_i32_e32 vcc, s2, v214
	s_and_saveexec_b64 s[2:3], vcc
	s_xor_b64 s[2:3], exec, s[2:3]
	v_add_u32_e32 v148, 0xffff8090, v214
	v_mov_b32_e32 v149, v0
	s_or_saveexec_b64 s[2:3], s[2:3]
	v_mov_b64_e32 v[158:159], s[82:83]
	s_xor_b64 exec, exec, s[2:3]
	s_cbranch_execz .LBB0_589
	s_waitcnt lgkmcnt(0)
	v_ashrrev_i32_e32 v147, 31, v146
	v_mov_b64_e32 v[158:159], s[96:97]
	v_mov_b64_e32 v[148:149], v[146:147]

; __device__ __forceinline__ unsigned cvt_pk_bf16(float lo, float hi) { unsigned r; asm volatile("v_cvt_pk_bf16_f32 %0, %1, %2" : "=v"(r) : "v"(lo), "v"(hi)); return r; }
; __device__ __forceinline__ void st16f_wt(void* p, f32x4 v) { asm volatile("global_store_dwordx4 %0, %1, off sc1\n\ts_nop 1" :: "v"(p), "v"(v) : "memory"); }
; __device__ __forceinline__ void st8_wt(void* p, u32x2w v) { asm volatile("global_store_dwordx2 %0, %1, off sc1\n\ts_nop 1" :: "v"(p), "v"(v) : "memory"); }
;     __device__ __forceinline__ void operator()(const f32x4 (&acc)[2][2][4][2], const Unit& u, int wr, int wc, int fr, int fq) const {
;     ...
;                 for (int n = 0; n < 2; ++n) { f32x4 x = xc[bj][n] + (acc[ai][bj][m][n] + bv[bj][n]) * alpha; st16f_wt(X + off + bj * HALF + n * 16, x);
;                     if (XB) { u32x2w w; w.x = cvt_pk_bf16(x[0], x[1]); w.y = cvt_pk_bf16(x[2], x[3]); st8_wt(XB + off + bj * HALF + n * 16, w); }
;                     s += (x[0] * x[0] + x[1] * x[1]) + (x[2] * x[2] + x[3] * x[3]); }
;             if (ssout) { s += __shfl_xor(s, 16); s += __shfl_xor(s, 32); if (fq == 0) unsafeAtomicAdd(ssout + row, s); } }
.LBB0_600:
	s_and_b64 vcc, exec, s[58:59]
	s_cbranch_vccnz .LBB0_604
	v_mul_f32_e32 v187, v187, v187
	v_mul_f32_e32 v175, v175, v175
	v_mul_f32_e32 v151, v151, v151
	v_fmac_f32_e32 v187, v186, v186
	v_mul_f32_e32 v186, v188, v188
	v_fmac_f32_e32 v175, v174, v174
	v_mul_f32_e32 v174, v176, v176
	v_mul_f32_e32 v163, v163, v163
	v_fmac_f32_e32 v151, v150, v150
	v_mul_f32_e32 v150, v152, v152
	v_fmac_f32_e32 v186, v189, v189
	v_fmac_f32_e32 v174, v177, v177
	v_fmac_f32_e32 v163, v162, v162
	v_mul_f32_e32 v162, v164, v164
	v_fmac_f32_e32 v150, v153, v153
	v_and_b32_e32 v152, 64, v233
	v_add_f32_e32 v186, v187, v186
	v_add_f32_e32 v174, v175, v174
	v_fmac_f32_e32 v162, v165, v165
	v_add_f32_e32 v150, v151, v150
	v_xor_b32_e32 v151, 16, v233
	v_add_u32_e32 v152, 64, v152
	v_add_f32_e32 v174, v186, v174
	v_add_f32_e32 v162, v163, v162
	v_cmp_lt_i32_e32 vcc, v151, v152
	v_add_f32_e32 v162, v174, v162
	v_add_f32_e32 v150, v162, v150
	v_cndmask_b32_e32 v151, v233, v151, vcc
	v_lshlrev_b32_e32 v151, 2, v151
	ds_bpermute_b32 v151, v151, v150
	s_waitcnt lgkmcnt(0)
	v_add_f32_e32 v150, v150, v151
	v_xor_b32_e32 v151, 32, v233
	v_cmp_lt_i32_e32 vcc, v151, v152
	s_nop 1
	v_cndmask_b32_e32 v151, v233, v151, vcc
	v_lshlrev_b32_e32 v151, 2, v151
	ds_bpermute_b32 v151, v151, v150
	s_waitcnt lgkmcnt(0)
	v_add_f32_e32 v150, v150, v151
	s_mov_b32 s2, 0
	s_mov_b32 s3, 0xffff0000
	v_cndmask_b32_e64 v243, v243, v150, s[2:3]
	v_lshl_add_u64 v[152:153], v[214:215], 2, s[98:99]
	v_and_b32_e32 v151, 0x30, v233
	v_lshlrev_b32_e32 v151, 2, v151
	v_add_co_u32_e32 v152, vcc, v152, v151
	s_nop 1
	v_addc_co_u32_e32 v153, vcc, 0, v153, vcc
	global_atomic_add_f32 v[152:153], v243, off
.LBB0_603:
.LBB0_604:
	v_or_b32_e32 v220, 32, v206
	s_mov_b64 s[2:3], -1
	s_and_b64 vcc, exec, s[60:61]
	v_mov_b64_e32 v[152:153], s[68:69]
	s_cbranch_vccnz .LBB0_610
	s_movk_i32 s2, 0x7fff
	v_cmp_lt_i32_e32 vcc, s2, v220
	s_and_saveexec_b64 s[2:3], vcc
	s_xor_b64 s[2:3], exec, s[2:3]
	s_cbranch_execz .LBB0_607
	v_add_u32_e32 v150, 0xffff80a0, v214
	s_waitcnt lgkmcnt(0)
	v_mov_b32_e32 v151, v0

; __device__ __forceinline__ unsigned cvt_pk_bf16(float lo, float hi) { unsigned r; asm volatile("v_cvt_pk_bf16_f32 %0, %1, %2" : "=v"(r) : "v"(lo), "v"(hi)); return r; }
; __device__ __forceinline__ void st16f_wt(void* p, f32x4 v) { asm volatile("global_store_dwordx4 %0, %1, off sc1\n\ts_nop 1" :: "v"(p), "v"(v) : "memory"); }
; __device__ __forceinline__ void st8_wt(void* p, u32x2w v) { asm volatile("global_store_dwordx2 %0, %1, off sc1\n\ts_nop 1" :: "v"(p), "v"(v) : "memory"); }
;     __device__ __forceinline__ void operator()(const f32x4 (&acc)[2][2][4][2], const Unit& u, int wr, int wc, int fr, int fq) const {
;     ...
;                 for (int n = 0; n < 2; ++n) { f32x4 x = xc[bj][n] + (acc[ai][bj][m][n] + bv[bj][n]) * alpha; st16f_wt(X + off + bj * HALF + n * 16, x);
;                     if (XB) { u32x2w w; w.x = cvt_pk_bf16(x[0], x[1]); w.y = cvt_pk_bf16(x[2], x[3]); st8_wt(XB + off + bj * HALF + n * 16, w); }
;                     s += (x[0] * x[0] + x[1] * x[1]) + (x[2] * x[2] + x[3] * x[3]); }
;             if (ssout) { s += __shfl_xor(s, 16); s += __shfl_xor(s, 32); if (fq == 0) unsafeAtomicAdd(ssout + row, s); } }
.LBB0_620:
	s_and_b64 vcc, exec, s[58:59]
	s_cbranch_vccnz .LBB0_624
	v_mul_f32_e32 v191, v191, v191
	v_mul_f32_e32 v179, v179, v179
	v_mul_f32_e32 v155, v155, v155
	v_fmac_f32_e32 v191, v190, v190
	v_mul_f32_e32 v190, v192, v192
	v_fmac_f32_e32 v179, v178, v178
	v_mul_f32_e32 v178, v180, v180
	v_mul_f32_e32 v167, v167, v167
	v_fmac_f32_e32 v155, v154, v154
	v_mul_f32_e32 v154, v156, v156
	v_fmac_f32_e32 v190, v193, v193
	v_fmac_f32_e32 v178, v181, v181
	v_fmac_f32_e32 v167, v166, v166
	v_mul_f32_e32 v166, v168, v168
	v_fmac_f32_e32 v154, v157, v157
	v_and_b32_e32 v156, 64, v233
	v_add_f32_e32 v190, v191, v190
	v_add_f32_e32 v178, v179, v178
	v_fmac_f32_e32 v166, v169, v169
	v_add_f32_e32 v154, v155, v154
	v_xor_b32_e32 v155, 16, v233
	v_add_u32_e32 v156, 64, v156
	v_add_f32_e32 v178, v190, v178
	v_add_f32_e32 v166, v167, v166
	v_cmp_lt_i32_e32 vcc, v155, v156
	v_add_f32_e32 v166, v178, v166
	v_add_f32_e32 v154, v166, v154
	v_cndmask_b32_e32 v155, v233, v155, vcc
	v_lshlrev_b32_e32 v155, 2, v155
	ds_bpermute_b32 v155, v155, v154
	s_waitcnt lgkmcnt(0)
	v_add_f32_e32 v154, v154, v155
	v_xor_b32_e32 v155, 32, v233
	v_cmp_lt_i32_e32 vcc, v155, v156
	s_nop 1
	v_cndmask_b32_e32 v155, v233, v155, vcc
	v_lshlrev_b32_e32 v155, 2, v155
	ds_bpermute_b32 v155, v155, v154
	s_waitcnt lgkmcnt(0)
	v_add_f32_e32 v154, v154, v155
	s_mov_b32 s2, 0xffff
	s_mov_b32 s3, 0
	v_cndmask_b32_e64 v243, v243, v154, s[2:3]
.LBB0_623:
.LBB0_624:
	v_or_b32_e32 v222, 48, v206
	s_mov_b64 s[2:3], -1
	s_and_b64 vcc, exec, s[60:61]
	v_mov_b64_e32 v[156:157], s[68:69]
	s_cbranch_vccnz .LBB0_630
	s_movk_i32 s2, 0x7fff
	v_cmp_lt_i32_e32 vcc, s2, v222
	s_and_saveexec_b64 s[2:3], vcc
	s_xor_b64 s[2:3], exec, s[2:3]
	s_cbranch_execz .LBB0_627
	v_add_u32_e32 v154, 0xffff80b0, v214
	s_waitcnt lgkmcnt(0)
	v_mov_b32_e32 v155, v0

; __device__ __forceinline__ unsigned cvt_pk_bf16(float lo, float hi) { unsigned r; asm volatile("v_cvt_pk_bf16_f32 %0, %1, %2" : "=v"(r) : "v"(lo), "v"(hi)); return r; }
; __device__ __forceinline__ void st16f_wt(void* p, f32x4 v) { asm volatile("global_store_dwordx4 %0, %1, off sc1\n\ts_nop 1" :: "v"(p), "v"(v) : "memory"); }
; __device__ __forceinline__ void st8_wt(void* p, u32x2w v) { asm volatile("global_store_dwordx2 %0, %1, off sc1\n\ts_nop 1" :: "v"(p), "v"(v) : "memory"); }
;     __device__ __forceinline__ void operator()(const f32x4 (&acc)[2][2][4][2], const Unit& u, int wr, int wc, int fr, int fq) const {
;     ...
;             for (int bj = 0; bj < 2; ++bj)
; #pragma unroll
;                 for (int n = 0; n < 2; ++n) { f32x4 x = xc[bj][n] + (acc[ai][bj][m][n] + bv[bj][n]) * alpha; st16f_wt(X + off + bj * HALF + n * 16, x);
;                     if (XB) { u32x2w w; w.x = cvt_pk_bf16(x[0], x[1]); w.y = cvt_pk_bf16(x[2], x[3]); st8_wt(XB + off + bj * HALF + n * 16, w); }
;                     s += (x[0] * x[0] + x[1] * x[1]) + (x[2] * x[2] + x[3] * x[3]); }
;             if (ssout) { s += __shfl_xor(s, 16); s += __shfl_xor(s, 32); if (fq == 0) unsafeAtomicAdd(ssout + row, s); } }
.LBB0_640:
	s_and_b64 vcc, exec, s[58:59]
	s_cbranch_vccnz .LBB0_644
	v_mul_f32_e32 v183, v183, v183
	v_mul_f32_e32 v171, v171, v171
	v_mul_f32_e32 v147, v147, v147
	v_fmac_f32_e32 v183, v182, v182
	v_mul_f32_e32 v182, v184, v184
	v_fmac_f32_e32 v171, v170, v170
	v_mul_f32_e32 v170, v172, v172
	v_mul_f32_e32 v159, v159, v159
	v_fmac_f32_e32 v147, v146, v146
	v_mul_f32_e32 v146, v148, v148
	v_fmac_f32_e32 v182, v185, v185
	v_fmac_f32_e32 v170, v173, v173
	v_fmac_f32_e32 v159, v158, v158
	v_mul_f32_e32 v158, v160, v160
	v_fmac_f32_e32 v146, v149, v149
	v_and_b32_e32 v148, 64, v233
	v_add_f32_e32 v182, v183, v182
	v_add_f32_e32 v170, v171, v170
	v_fmac_f32_e32 v158, v161, v161
	v_add_f32_e32 v146, v147, v146
	v_xor_b32_e32 v147, 16, v233
	v_add_u32_e32 v148, 64, v148
	v_add_f32_e32 v170, v182, v170
	v_add_f32_e32 v158, v159, v158
	v_cmp_lt_i32_e32 vcc, v147, v148
	v_add_f32_e32 v158, v170, v158
	v_add_f32_e32 v146, v158, v146
	v_cndmask_b32_e32 v147, v233, v147, vcc
	v_lshlrev_b32_e32 v147, 2, v147
	ds_bpermute_b32 v147, v147, v146
	s_waitcnt lgkmcnt(0)
	v_add_f32_e32 v146, v146, v147
	v_xor_b32_e32 v147, 32, v233
	v_cmp_lt_i32_e32 vcc, v147, v148
	s_nop 1
	v_cndmask_b32_e32 v147, v233, v147, vcc
	v_lshlrev_b32_e32 v147, 2, v147
	ds_bpermute_b32 v147, v147, v146
	s_waitcnt lgkmcnt(0)
	v_add_f32_e32 v146, v146, v147
	s_mov_b32 s2, 0xffff0000
	s_mov_b32 s3, 0
	v_cndmask_b32_e64 v243, v243, v146, s[2:3]
.LBB0_643:
.LBB0_644:
	s_waitcnt lgkmcnt(0)
	v_lshlrev_b64 v[146:147], 10, v[220:221]
	v_lshl_add_u64 v[158:159], v[146:147], 0, v[218:219]
	v_pk_add_f32 v[146:147], v[48:49], v[144:145]
	v_pk_add_f32 v[160:161], v[46:47], v[142:143]
	s_waitcnt vmcnt(7)
	v_pk_fma_f32 v[148:149], v[146:147], s[94:95], v[188:189]
	v_pk_fma_f32 v[146:147], v[160:161], s[14:15], v[186:187]
	v_lshl_add_u64 v[172:173], v[158:159], 2, s[68:69]
	global_store_dwordx4 v[172:173], v[146:149], off sc1
	s_nop 1
	s_and_b64 vcc, exec, s[42:43]
	v_lshl_add_u64 v[170:171], v[158:159], 1, s[88:89]
	s_cbranch_vccz .LBB0_646

; __device__ __forceinline__ unsigned cvt_pk_bf16(float lo, float hi) { unsigned r; asm volatile("v_cvt_pk_bf16_f32 %0, %1, %2" : "=v"(r) : "v"(lo), "v"(hi)); return r; }
; __device__ __forceinline__ void st16f_wt(void* p, f32x4 v) { asm volatile("global_store_dwordx4 %0, %1, off sc1\n\ts_nop 1" :: "v"(p), "v"(v) : "memory"); }
; __device__ __forceinline__ void st8_wt(void* p, u32x2w v) { asm volatile("global_store_dwordx2 %0, %1, off sc1\n\ts_nop 1" :: "v"(p), "v"(v) : "memory"); }
;     __device__ __forceinline__ void operator()(const f32x4 (&acc)[2][2][4][2], const Unit& u, int wr, int wc, int fr, int fq) const {
;     ...
;             for (int bj = 0; bj < 2; ++bj)
; #pragma unroll
;                 for (int n = 0; n < 2; ++n) { f32x4 x = xc[bj][n] + (acc[ai][bj][m][n] + bv[bj][n]) * alpha; st16f_wt(X + off + bj * HALF + n * 16, x);
;                     if (XB) { u32x2w w; w.x = cvt_pk_bf16(x[0], x[1]); w.y = cvt_pk_bf16(x[2], x[3]); st8_wt(XB + off + bj * HALF + n * 16, w); }
;                     s += (x[0] * x[0] + x[1] * x[1]) + (x[2] * x[2] + x[3] * x[3]); }
;             if (ssout) { s += __shfl_xor(s, 16); s += __shfl_xor(s, 32); if (fq == 0) unsafeAtomicAdd(ssout + row, s); } }
.LBB0_652:
	s_and_b64 vcc, exec, s[58:59]
	s_cbranch_vccnz .LBB0_656
	v_mul_f32_e32 v147, v147, v147
	v_fmac_f32_e32 v147, v146, v146
	v_mul_f32_e32 v146, v148, v148
	v_fmac_f32_e32 v146, v149, v149
	v_add_f32_e32 v146, v147, v146
	v_mul_f32_e32 v147, v159, v159
	v_mul_f32_e32 v148, v160, v160
	v_fmac_f32_e32 v147, v158, v158
	v_fmac_f32_e32 v148, v161, v161
	v_add_f32_e32 v147, v147, v148
	v_add_f32_e32 v146, v146, v147
	v_mul_f32_e32 v147, v163, v163
	v_mul_f32_e32 v148, v164, v164
	v_fmac_f32_e32 v147, v162, v162
	v_fmac_f32_e32 v148, v165, v165
	v_add_f32_e32 v147, v147, v148
	v_add_f32_e32 v146, v146, v147
	v_mul_f32_e32 v147, v151, v151
	v_mul_f32_e32 v148, v152, v152
	v_fmac_f32_e32 v147, v150, v150
	v_fmac_f32_e32 v148, v153, v153
	v_add_f32_e32 v147, v147, v148
	v_and_b32_e32 v148, 64, v233
	v_add_f32_e32 v146, v146, v147
	v_xor_b32_e32 v147, 16, v233
	v_add_u32_e32 v148, 64, v148
	v_cmp_lt_i32_e32 vcc, v147, v148
	s_nop 1
	v_cndmask_b32_e32 v147, v233, v147, vcc
	v_lshlrev_b32_e32 v147, 2, v147
	ds_bpermute_b32 v147, v147, v146
	s_waitcnt lgkmcnt(0)
	v_add_f32_e32 v146, v146, v147
	v_xor_b32_e32 v147, 32, v233
	v_cmp_lt_i32_e32 vcc, v147, v148
	s_nop 1
	v_cndmask_b32_e32 v147, v233, v147, vcc
	v_lshlrev_b32_e32 v147, 2, v147
	ds_bpermute_b32 v147, v147, v146
	s_waitcnt lgkmcnt(0)
	v_add_f32_e32 v146, v146, v147
	s_mov_b32 s2, 0
	s_mov_b32 s3, 0xffff
	v_cndmask_b32_e64 v243, v243, v146, s[2:3]
.LBB0_655:
.LBB0_656:
	s_waitcnt lgkmcnt(0)
	v_lshlrev_b64 v[146:147], 10, v[222:223]
	v_lshl_add_u64 v[146:147], v[146:147], 0, v[218:219]
	v_pk_add_f32 v[144:145], v[40:41], v[144:145]
	v_pk_add_f32 v[142:143], v[38:39], v[142:143]
	s_waitcnt vmcnt(3)
	v_pk_fma_f32 v[144:145], v[144:145], s[94:95], v[192:193]
	v_pk_fma_f32 v[142:143], v[142:143], s[14:15], v[190:191]
	v_lshl_add_u64 v[148:149], v[146:147], 2, s[68:69]
	global_store_dwordx4 v[148:149], v[142:145], off sc1
	s_nop 1
	s_and_b64 vcc, exec, s[42:43]
	v_lshl_add_u64 v[146:147], v[146:147], 1, s[88:89]
	s_cbranch_vccz .LBB0_658

;     __device__ __forceinline__ void flush() const { if (*pendp) { asm volatile("s_waitcnt vmcnt(0)" ::: "memory"); publish(*pendp); *pendp = nullptr; } }
; __device__ __forceinline__ unsigned cvt_pk_bf16(float lo, float hi) { unsigned r; asm volatile("v_cvt_pk_bf16_f32 %0, %1, %2" : "=v"(r) : "v"(lo), "v"(hi)); return r; }
; __device__ __forceinline__ void st16f_wt(void* p, f32x4 v) { asm volatile("global_store_dwordx4 %0, %1, off sc1\n\ts_nop 1" :: "v"(p), "v"(v) : "memory"); }
; __device__ __forceinline__ void st8_wt(void* p, u32x2w v) { asm volatile("global_store_dwordx2 %0, %1, off sc1\n\ts_nop 1" :: "v"(p), "v"(v) : "memory"); }
;     __device__ __forceinline__ void done(const Unit& u, bool has_next) const {
;         unsigned* m = mine ? mine + 16 * u.pm : nullptr;
;         if (has_next) { flush(); *pendp = m; }
;     __device__ __forceinline__ void operator()(const f32x4 (&acc)[2][2][4][2], const Unit& u, int wr, int wc, int fr, int fq) const {
;     ...
;                 for (int n = 0; n < 2; ++n) { f32x4 x = xc[bj][n] + (acc[ai][bj][m][n] + bv[bj][n]) * alpha; st16f_wt(X + off + bj * HALF + n * 16, x);
;                     if (XB) { u32x2w w; w.x = cvt_pk_bf16(x[0], x[1]); w.y = cvt_pk_bf16(x[2], x[3]); st8_wt(XB + off + bj * HALF + n * 16, w); }
;                     s += (x[0] * x[0] + x[1] * x[1]) + (x[2] * x[2] + x[3] * x[3]); }
;             if (ssout) { s += __shfl_xor(s, 16); s += __shfl_xor(s, 32); if (fq == 0) unsafeAtomicAdd(ssout + row, s); } }
.LBB0_664:
	s_and_b64 vcc, exec, s[58:59]
	s_cbranch_vccnz .LBB0_668
	v_mul_f32_e32 v135, v135, v135
	v_mul_f32_e32 v143, v143, v143
	v_fmac_f32_e32 v135, v134, v134
	v_mul_f32_e32 v134, v136, v136
	v_mul_f32_e32 v131, v131, v131
	v_fmac_f32_e32 v143, v142, v142
	v_mul_f32_e32 v142, v144, v144
	v_fmac_f32_e32 v134, v137, v137
	v_fmac_f32_e32 v131, v130, v130
	v_mul_f32_e32 v130, v132, v132
	v_fmac_f32_e32 v142, v145, v145
	v_add_f32_e32 v134, v135, v134
	v_mul_f32_e32 v135, v139, v139
	v_mul_f32_e32 v136, v140, v140
	v_fmac_f32_e32 v130, v133, v133
	v_and_b32_e32 v132, 64, v233
	v_add_f32_e32 v142, v143, v142
	v_fmac_f32_e32 v135, v138, v138
	v_fmac_f32_e32 v136, v141, v141
	v_add_f32_e32 v130, v131, v130
	v_xor_b32_e32 v131, 16, v233
	v_add_u32_e32 v132, 64, v132
	v_add_f32_e32 v134, v142, v134
	v_add_f32_e32 v135, v135, v136
	v_cmp_lt_i32_e32 vcc, v131, v132
	v_add_f32_e32 v134, v134, v135
	v_add_f32_e32 v130, v134, v130
	v_cndmask_b32_e32 v131, v233, v131, vcc
	v_lshlrev_b32_e32 v131, 2, v131
	ds_bpermute_b32 v131, v131, v130
	s_waitcnt lgkmcnt(0)
	v_add_f32_e32 v130, v130, v131
	v_xor_b32_e32 v131, 32, v233
	v_cmp_lt_i32_e32 vcc, v131, v132
	s_nop 1
	v_cndmask_b32_e32 v131, v233, v131, vcc
	v_lshlrev_b32_e32 v131, 2, v131
	ds_bpermute_b32 v131, v131, v130
	s_waitcnt lgkmcnt(0)
	v_add_f32_e32 v130, v130, v131
	s_mov_b32 s2, 0
	s_mov_b32 s3, 0xffff0000
	v_cndmask_b32_e64 v243, v243, v130, s[2:3]
	v_lshl_add_u64 v[132:133], v[214:215], 2, s[98:99]
	v_and_b32_e32 v131, 0x30, v233
	v_lshlrev_b32_e32 v131, 2, v131
	v_add_co_u32_e32 v132, vcc, v132, v131
	s_nop 1
	v_addc_co_u32_e32 v133, vcc, 0, v133, vcc
	global_atomic_add_f32 v[132:133], v243, off offset:512
.LBB0_667:
.LBB0_668:
	s_lshl_b32 s2, s85, 4
	s_ashr_i32 s3, s2, 31
	s_lshl_b64 s[2:3], s[2:3], 2
	v_readlane_b32 s36, v255, 11
	v_readlane_b32 s37, v255, 12
	s_add_u32 s36, s36, s2
	s_addc_u32 s37, s37, s3
	s_and_b64 s[2:3], s[4:5], exec
	s_cselect_b32 s3, 0, s37
	s_cselect_b32 s2, 0, s36
	s_and_b64 vcc, exec, s[56:57]
	s_mov_b64 s[38:39], -1
	s_cbranch_vccnz .LBB0_674
	v_mov_b64_e32 v[206:207], s[2:3]
	s_cbranch_execz .LBB0_675
